# attention phase: static s_setprio 1 for waves 0-3 (the other half than tried before), reset at phase end
# baseline (speedup 1.0000x reference)
.LBB0_1295:
	s_or_b64 exec, exec, s[0:1]
	s_mov_b64 s[0:1], s[66:67]
	s_mov_b64 s[6:7], s[68:69]
	s_waitcnt lgkmcnt(0)
	s_barrier
	v_readfirstlane_b32 s98, v194
	s_lshr_b32 s98, s98, 6
	s_cmp_lt_u32 s98, 4
	s_cbranch_scc0 .Laprio_0
	s_setprio 1

.LBB0_2905:
	s_or_b64 exec, exec, s[0:1]
	s_mov_b64 s[0:1], s[66:67]
	s_mov_b64 s[8:9], s[68:69]
	s_waitcnt lgkmcnt(0)
	s_barrier
	v_readfirstlane_b32 s98, v194
	s_lshr_b32 s98, s98, 6
	s_cmp_lt_u32 s98, 4
	s_cbranch_scc0 .Laprio_1
	s_setprio 1
